# speedup vs baseline: 1.0010x; 1.0010x over previous
; #define GAS __attribute__((address_space(1)))
; __device__ __forceinline__ uint2 pack4(f32x4 v) { return make_uint2(pack2(v[0], v[1]), pack2(v[2], v[3])); }
; template <int MODE>
; __device__ __forceinline__ void epi_elem(char* ws, float* outp, const float* b_gate, int g0, int rl, int col, f32x4 v) {
;     ...
;   } else if (MODE == E_K) {
;     int lc = col & 1023;
;     *(GAS uint2*)((u16*)(ws + W_K) + (size_t)rl * 1024 + lc) = pack4(v);
;     int rg = g0 + rl;
;     float* o = rg < NPROMPT ? outp + O_KP + (size_t)rg * 1024 : outp + O_KS + (size_t)(rg - NPROMPT) * 1024;
;     __builtin_nontemporal_store(v, (GAS f32x4*)(o + lc));
; template <int MODE>
; __device__ __forceinline__ void epi_store(char* ws, float* outp, const float* b_gate, int g0, const f32x4 (&acc)[2][2][4][2], int rbase, int cbase) {
; #pragma unroll
;   for (int ai = 0; ai < 2; ++ai)
; #pragma unroll
;     for (int bj = 0; bj < 2; ++bj)
; #pragma unroll
;       for (int m = 0; m < 4; ++m) {
; #pragma unroll
;         for (int n = 0; n < 2; ++n)
;           epi_elem<MODE>(ws, outp, b_gate, g0, rbase + ai * HALF + m * 16, cbase + bj * HALF + n * 16, acc[ai][bj][m][n]);
;         if ((m & 1) && (MODE != E_M1 && MODE != E_MG)) __builtin_amdgcn_sched_barrier(0);
;         if (m == 3 && (MODE == E_M1 || MODE == E_MG)) __builtin_amdgcn_sched_barrier(0);
;       }
.LBB0_603:
	s_and_b64 vcc, exec, s[12:13]
	s_cbranch_vccz .LBB0_615
	s_cmp_gt_i32 s16, 1
	s_mov_b64 s[8:9], -1
	s_cbranch_scc0 .LBB0_610
	s_cmp_gt_i32 s16, 2
	s_cbranch_scc0 .LBB0_607
	s_mov_b32 s16, 0x8000
	v_bfe_u32 v141, v184, 2, 2
	v_and_b32_e32 v143, 1, v141
	v_lshrrev_b32_e32 v187, 1, v141
	v_lshlrev_b32_e32 v143, 4, v143
	v_lshl_add_u32 v143, v187, 3, v143
	v_lshlrev_b32_e32 v141, 2, v141
	v_sub_u32_e32 v143, v143, v141
	v_add_u32_e32 v143, v140, v143
	v_and_b32_e32 v143, 0x3ff, v143
	v_lshlrev_b32_e32 v141, 11, v142
	v_lshl_add_u32 v250, v143, 1, v141
	v_add_u32_e32 v251, 0x8000, v250
	v_add_u32_e32 v252, 0x10000, v250
	v_add_u32_e32 v253, 0x18000, v250
	s_add_u32 s4, s2, 0x128c0000
	s_addc_u32 s5, s3, 0
	s_add_u32 s8, s2, 0x12900000
	s_addc_u32 s9, s3, 0
	s_add_u32 s14, s6, 0x80000
	s_addc_u32 s15, s7, 0
	s_mov_b32 s17, 0x10000
	v_add_u32_e32 v187, s16, v142
	v_and_b32_e32 v141, 0x3ff, v140
	v_cmp_gt_i32_e32 vcc, s17, v187
	v_add_u32_e32 v188, 0xffff0000, v187
	v_lshlrev_b32_e32 v141, 2, v141
	s_nop 0
	v_cndmask_b32_e32 v187, v188, v187, vcc
	v_cndmask_b32_e32 v188, v207, v208, vcc
	v_lshl_add_u32 v187, v187, 12, v188
	v_add_u32_e32 v246, v187, v141
	v_add_u32_e32 v247, 0x10000, v246
	v_add_u32_e32 v248, 0x20000, v246
	v_add_u32_e32 v249, 0x30000, v246
	v_and_b32_e32 v187, 8, v1
	v_cmp_eq_u32_e32 vcc, 0, v187
	v_mov_b32_e32 v188, 0xffff8040
	v_mov_b32_e32 v189, 64
	v_mov_b32_e32 v190, 0x8000
	v_cndmask_b32_e32 v188, v188, v0, vcc
	v_cndmask_b32_e32 v189, v189, v190, vcc
	v_cvt_pk_bf16_f32 v144, v126, v127
	v_cvt_pk_bf16_f32 v145, v128, v129
	v_cvt_pk_bf16_f32 v146, v122, v123
	v_cvt_pk_bf16_f32 v147, v124, v125
	v_mov_b32_e32 v176, v126
	v_mov_b32_e32 v177, v127
	v_mov_b32_e32 v178, v128
	v_mov_b32_e32 v179, v129
	v_mov_b32_e32 v180, v122
	v_mov_b32_e32 v181, v123
	v_mov_b32_e32 v182, v124
	v_mov_b32_e32 v183, v125
	v_mov_b32_dpp v176, v122 row_ror:8 row_mask:0xf bank_mask:0xc
	v_mov_b32_dpp v177, v123 row_ror:8 row_mask:0xf bank_mask:0xc
	v_mov_b32_dpp v178, v124 row_ror:8 row_mask:0xf bank_mask:0xc
	v_mov_b32_dpp v179, v125 row_ror:8 row_mask:0xf bank_mask:0xc
	v_mov_b32_dpp v180, v126 row_ror:8 row_mask:0xf bank_mask:0x3
	v_mov_b32_dpp v181, v127 row_ror:8 row_mask:0xf bank_mask:0x3
	v_mov_b32_dpp v182, v128 row_ror:8 row_mask:0xf bank_mask:0x3
	v_mov_b32_dpp v183, v129 row_ror:8 row_mask:0xf bank_mask:0x3
	v_add_u32_e32 v191, v246, v188
	v_add_u32_e32 v192, v246, v189
	global_store_dwordx4 v191, v[176:179], s[6:7] nt
	global_store_dwordx4 v192, v[180:183], s[6:7] nt
	v_cvt_pk_bf16_f32 v148, v118, v119
	v_cvt_pk_bf16_f32 v149, v120, v121
	v_cvt_pk_bf16_f32 v150, v114, v115
	v_cvt_pk_bf16_f32 v151, v116, v117
	v_mov_b32_e32 v214, v118
	v_mov_b32_e32 v215, v119
	v_mov_b32_e32 v216, v120
	v_mov_b32_e32 v217, v121
	v_mov_b32_e32 v218, v114
	v_mov_b32_e32 v219, v115
	v_mov_b32_e32 v220, v116
	v_mov_b32_e32 v221, v117
	v_mov_b32_dpp v214, v114 row_ror:8 row_mask:0xf bank_mask:0xc
	v_mov_b32_dpp v215, v115 row_ror:8 row_mask:0xf bank_mask:0xc
	v_mov_b32_dpp v216, v116 row_ror:8 row_mask:0xf bank_mask:0xc
	v_mov_b32_dpp v217, v117 row_ror:8 row_mask:0xf bank_mask:0xc
	v_mov_b32_dpp v218, v118 row_ror:8 row_mask:0xf bank_mask:0x3
	v_mov_b32_dpp v219, v119 row_ror:8 row_mask:0xf bank_mask:0x3
	v_mov_b32_dpp v220, v120 row_ror:8 row_mask:0xf bank_mask:0x3
	v_mov_b32_dpp v221, v121 row_ror:8 row_mask:0xf bank_mask:0x3
	v_add_u32_e32 v191, v247, v188
	v_add_u32_e32 v192, v247, v189
	global_store_dwordx4 v191, v[214:217], s[6:7] nt
	global_store_dwordx4 v192, v[218:221], s[6:7] nt
	v_permlane16_swap_b32_e32 v144, v146
	v_permlane16_swap_b32_e32 v145, v147
	global_store_dwordx4 v250, v[144:147], s[4:5]
	v_cvt_pk_bf16_f32 v152, v110, v111
	v_cvt_pk_bf16_f32 v153, v112, v113
	v_cvt_pk_bf16_f32 v154, v106, v107
	v_cvt_pk_bf16_f32 v155, v108, v109
	v_mov_b32_e32 v176, v110
	v_mov_b32_e32 v177, v111
	v_mov_b32_e32 v178, v112
	v_mov_b32_e32 v179, v113
	v_mov_b32_e32 v180, v106
	v_mov_b32_e32 v181, v107
	v_mov_b32_e32 v182, v108
	v_mov_b32_e32 v183, v109
	v_mov_b32_dpp v176, v106 row_ror:8 row_mask:0xf bank_mask:0xc
	v_mov_b32_dpp v177, v107 row_ror:8 row_mask:0xf bank_mask:0xc
	v_mov_b32_dpp v178, v108 row_ror:8 row_mask:0xf bank_mask:0xc
	v_mov_b32_dpp v179, v109 row_ror:8 row_mask:0xf bank_mask:0xc
	v_mov_b32_dpp v180, v110 row_ror:8 row_mask:0xf bank_mask:0x3
	v_mov_b32_dpp v181, v111 row_ror:8 row_mask:0xf bank_mask:0x3
	v_mov_b32_dpp v182, v112 row_ror:8 row_mask:0xf bank_mask:0x3
	v_mov_b32_dpp v183, v113 row_ror:8 row_mask:0xf bank_mask:0x3
	v_add_u32_e32 v191, v248, v188
	v_add_u32_e32 v192, v248, v189
	global_store_dwordx4 v191, v[176:179], s[6:7] nt
	global_store_dwordx4 v192, v[180:183], s[6:7] nt
	v_permlane16_swap_b32_e32 v148, v150
	v_permlane16_swap_b32_e32 v149, v151
	global_store_dwordx4 v251, v[148:151], s[4:5]
	v_cvt_pk_bf16_f32 v156, v102, v103
	v_cvt_pk_bf16_f32 v157, v104, v105
	v_cvt_pk_bf16_f32 v158, v98, v99
	v_cvt_pk_bf16_f32 v159, v100, v101
	v_mov_b32_e32 v214, v102
	v_mov_b32_e32 v215, v103
	v_mov_b32_e32 v216, v104
	v_mov_b32_e32 v217, v105
	v_mov_b32_e32 v218, v98
	v_mov_b32_e32 v219, v99
	v_mov_b32_e32 v220, v100
	v_mov_b32_e32 v221, v101
	v_mov_b32_dpp v214, v98 row_ror:8 row_mask:0xf bank_mask:0xc
	v_mov_b32_dpp v215, v99 row_ror:8 row_mask:0xf bank_mask:0xc
	v_mov_b32_dpp v216, v100 row_ror:8 row_mask:0xf bank_mask:0xc
	v_mov_b32_dpp v217, v101 row_ror:8 row_mask:0xf bank_mask:0xc
	v_mov_b32_dpp v218, v102 row_ror:8 row_mask:0xf bank_mask:0x3
	v_mov_b32_dpp v219, v103 row_ror:8 row_mask:0xf bank_mask:0x3
	v_mov_b32_dpp v220, v104 row_ror:8 row_mask:0xf bank_mask:0x3
	v_mov_b32_dpp v221, v105 row_ror:8 row_mask:0xf bank_mask:0x3
; #define GAS __attribute__((address_space(1)))
; __device__ __forceinline__ uint2 pack4(f32x4 v) { return make_uint2(pack2(v[0], v[1]), pack2(v[2], v[3])); }
; template <int MODE>
; __device__ __forceinline__ void epi_elem(char* ws, float* outp, const float* b_gate, int g0, int rl, int col, f32x4 v) {
;     ...
;   } else if (MODE == E_K) {
;     int lc = col & 1023;
;     *(GAS uint2*)((u16*)(ws + W_K) + (size_t)rl * 1024 + lc) = pack4(v);
;     int rg = g0 + rl;
;     float* o = rg < NPROMPT ? outp + O_KP + (size_t)rg * 1024 : outp + O_KS + (size_t)(rg - NPROMPT) * 1024;
;     __builtin_nontemporal_store(v, (GAS f32x4*)(o + lc));
; template <int MODE>
; __device__ __forceinline__ void epi_store(char* ws, float* outp, const float* b_gate, int g0, const f32x4 (&acc)[2][2][4][2], int rbase, int cbase) {
; #pragma unroll
;   for (int ai = 0; ai < 2; ++ai)
; #pragma unroll
;     for (int bj = 0; bj < 2; ++bj)
; #pragma unroll
;       for (int m = 0; m < 4; ++m) {
; #pragma unroll
;         for (int n = 0; n < 2; ++n)
;           epi_elem<MODE>(ws, outp, b_gate, g0, rbase + ai * HALF + m * 16, cbase + bj * HALF + n * 16, acc[ai][bj][m][n]);
;         if ((m & 1) && (MODE != E_M1 && MODE != E_MG)) __builtin_amdgcn_sched_barrier(0);
;         if (m == 3 && (MODE == E_M1 || MODE == E_MG)) __builtin_amdgcn_sched_barrier(0);
;       }
	v_add_u32_e32 v191, v249, v188
	v_add_u32_e32 v192, v249, v189
	global_store_dwordx4 v191, v[214:217], s[6:7] nt
	global_store_dwordx4 v192, v[218:221], s[6:7] nt
	v_permlane16_swap_b32_e32 v152, v154
	v_permlane16_swap_b32_e32 v153, v155
	global_store_dwordx4 v252, v[152:155], s[4:5]
	v_cvt_pk_bf16_f32 v144, v94, v95
	v_cvt_pk_bf16_f32 v145, v96, v97
	v_cvt_pk_bf16_f32 v146, v90, v91
	v_cvt_pk_bf16_f32 v147, v92, v93
	v_mov_b32_e32 v176, v94
	v_mov_b32_e32 v177, v95
	v_mov_b32_e32 v178, v96
	v_mov_b32_e32 v179, v97
	v_mov_b32_e32 v180, v90
	v_mov_b32_e32 v181, v91
	v_mov_b32_e32 v182, v92
	v_mov_b32_e32 v183, v93
	v_mov_b32_dpp v176, v90 row_ror:8 row_mask:0xf bank_mask:0xc
	v_mov_b32_dpp v177, v91 row_ror:8 row_mask:0xf bank_mask:0xc
	v_mov_b32_dpp v178, v92 row_ror:8 row_mask:0xf bank_mask:0xc
	v_mov_b32_dpp v179, v93 row_ror:8 row_mask:0xf bank_mask:0xc
	v_mov_b32_dpp v180, v94 row_ror:8 row_mask:0xf bank_mask:0x3
	v_mov_b32_dpp v181, v95 row_ror:8 row_mask:0xf bank_mask:0x3
	v_mov_b32_dpp v182, v96 row_ror:8 row_mask:0xf bank_mask:0x3
	v_mov_b32_dpp v183, v97 row_ror:8 row_mask:0xf bank_mask:0x3
	v_add_u32_e32 v191, v246, v188
	v_add_u32_e32 v192, v246, v189
	global_store_dwordx4 v191, v[176:179], s[6:7] offset:512 nt
	global_store_dwordx4 v192, v[180:183], s[6:7] offset:512 nt
	v_permlane16_swap_b32_e32 v156, v158
	v_permlane16_swap_b32_e32 v157, v159
	global_store_dwordx4 v253, v[156:159], s[4:5]
	v_cvt_pk_bf16_f32 v148, v86, v87
	v_cvt_pk_bf16_f32 v149, v88, v89
	v_cvt_pk_bf16_f32 v150, v82, v83
	v_cvt_pk_bf16_f32 v151, v84, v85
	v_mov_b32_e32 v214, v86
	v_mov_b32_e32 v215, v87
	v_mov_b32_e32 v216, v88
	v_mov_b32_e32 v217, v89
	v_mov_b32_e32 v218, v82
	v_mov_b32_e32 v219, v83
	v_mov_b32_e32 v220, v84
	v_mov_b32_e32 v221, v85
	v_mov_b32_dpp v214, v82 row_ror:8 row_mask:0xf bank_mask:0xc
	v_mov_b32_dpp v215, v83 row_ror:8 row_mask:0xf bank_mask:0xc
	v_mov_b32_dpp v216, v84 row_ror:8 row_mask:0xf bank_mask:0xc
	v_mov_b32_dpp v217, v85 row_ror:8 row_mask:0xf bank_mask:0xc
	v_mov_b32_dpp v218, v86 row_ror:8 row_mask:0xf bank_mask:0x3
	v_mov_b32_dpp v219, v87 row_ror:8 row_mask:0xf bank_mask:0x3
	v_mov_b32_dpp v220, v88 row_ror:8 row_mask:0xf bank_mask:0x3
	v_mov_b32_dpp v221, v89 row_ror:8 row_mask:0xf bank_mask:0x3
	v_add_u32_e32 v191, v247, v188
	v_add_u32_e32 v192, v247, v189
	global_store_dwordx4 v191, v[214:217], s[6:7] offset:512 nt
	global_store_dwordx4 v192, v[218:221], s[6:7] offset:512 nt
	v_permlane16_swap_b32_e32 v144, v146
	v_permlane16_swap_b32_e32 v145, v147
	global_store_dwordx4 v250, v[144:147], s[4:5] offset:256
	v_cvt_pk_bf16_f32 v152, v78, v79
	v_cvt_pk_bf16_f32 v153, v80, v81
	v_cvt_pk_bf16_f32 v154, v74, v75
	v_cvt_pk_bf16_f32 v155, v76, v77
	v_mov_b32_e32 v176, v78
	v_mov_b32_e32 v177, v79
	v_mov_b32_e32 v178, v80
	v_mov_b32_e32 v179, v81
	v_mov_b32_e32 v180, v74
	v_mov_b32_e32 v181, v75
	v_mov_b32_e32 v182, v76
	v_mov_b32_e32 v183, v77
	v_mov_b32_dpp v176, v74 row_ror:8 row_mask:0xf bank_mask:0xc
	v_mov_b32_dpp v177, v75 row_ror:8 row_mask:0xf bank_mask:0xc
	v_mov_b32_dpp v178, v76 row_ror:8 row_mask:0xf bank_mask:0xc
	v_mov_b32_dpp v179, v77 row_ror:8 row_mask:0xf bank_mask:0xc
	v_mov_b32_dpp v180, v78 row_ror:8 row_mask:0xf bank_mask:0x3
	v_mov_b32_dpp v181, v79 row_ror:8 row_mask:0xf bank_mask:0x3
	v_mov_b32_dpp v182, v80 row_ror:8 row_mask:0xf bank_mask:0x3
	v_mov_b32_dpp v183, v81 row_ror:8 row_mask:0xf bank_mask:0x3
	v_add_u32_e32 v191, v248, v188
	v_add_u32_e32 v192, v248, v189
	global_store_dwordx4 v191, v[176:179], s[6:7] offset:512 nt
	global_store_dwordx4 v192, v[180:183], s[6:7] offset:512 nt
	v_permlane16_swap_b32_e32 v148, v150
	v_permlane16_swap_b32_e32 v149, v151
	global_store_dwordx4 v251, v[148:151], s[4:5] offset:256
	v_cvt_pk_bf16_f32 v156, v70, v71
	v_cvt_pk_bf16_f32 v157, v72, v73
	v_cvt_pk_bf16_f32 v158, v66, v67
	v_cvt_pk_bf16_f32 v159, v68, v69
	v_mov_b32_e32 v214, v70
	v_mov_b32_e32 v215, v71
	v_mov_b32_e32 v216, v72
	v_mov_b32_e32 v217, v73
	v_mov_b32_e32 v218, v66
	v_mov_b32_e32 v219, v67
	v_mov_b32_e32 v220, v68
	v_mov_b32_e32 v221, v69
	v_mov_b32_dpp v214, v66 row_ror:8 row_mask:0xf bank_mask:0xc
	v_mov_b32_dpp v215, v67 row_ror:8 row_mask:0xf bank_mask:0xc
	v_mov_b32_dpp v216, v68 row_ror:8 row_mask:0xf bank_mask:0xc
	v_mov_b32_dpp v217, v69 row_ror:8 row_mask:0xf bank_mask:0xc
	v_mov_b32_dpp v218, v70 row_ror:8 row_mask:0xf bank_mask:0x3
	v_mov_b32_dpp v219, v71 row_ror:8 row_mask:0xf bank_mask:0x3
	v_mov_b32_dpp v220, v72 row_ror:8 row_mask:0xf bank_mask:0x3
	v_mov_b32_dpp v221, v73 row_ror:8 row_mask:0xf bank_mask:0x3
	v_add_u32_e32 v191, v249, v188
	v_add_u32_e32 v192, v249, v189
	global_store_dwordx4 v191, v[214:217], s[6:7] offset:512 nt
	global_store_dwordx4 v192, v[218:221], s[6:7] offset:512 nt
	v_permlane16_swap_b32_e32 v152, v154
	v_permlane16_swap_b32_e32 v153, v155
	global_store_dwordx4 v252, v[152:155], s[4:5] offset:256
	v_cvt_pk_bf16_f32 v144, v62, v63
	v_cvt_pk_bf16_f32 v145, v64, v65
	v_cvt_pk_bf16_f32 v146, v58, v59
	v_cvt_pk_bf16_f32 v147, v60, v61
	v_mov_b32_e32 v176, v62
	v_mov_b32_e32 v177, v63
	v_mov_b32_e32 v178, v64
	v_mov_b32_e32 v179, v65
	v_mov_b32_e32 v180, v58
	v_mov_b32_e32 v181, v59
	v_mov_b32_e32 v182, v60
	v_mov_b32_e32 v183, v61
	v_mov_b32_dpp v176, v58 row_ror:8 row_mask:0xf bank_mask:0xc
	v_mov_b32_dpp v177, v59 row_ror:8 row_mask:0xf bank_mask:0xc
	v_mov_b32_dpp v178, v60 row_ror:8 row_mask:0xf bank_mask:0xc
	v_mov_b32_dpp v179, v61 row_ror:8 row_mask:0xf bank_mask:0xc
	v_mov_b32_dpp v180, v62 row_ror:8 row_mask:0xf bank_mask:0x3
	v_mov_b32_dpp v181, v63 row_ror:8 row_mask:0xf bank_mask:0x3
	v_mov_b32_dpp v182, v64 row_ror:8 row_mask:0xf bank_mask:0x3
; #define GAS __attribute__((address_space(1)))
; __device__ __forceinline__ uint2 pack4(f32x4 v) { return make_uint2(pack2(v[0], v[1]), pack2(v[2], v[3])); }
; template <int MODE>
; __device__ __forceinline__ void epi_elem(char* ws, float* outp, const float* b_gate, int g0, int rl, int col, f32x4 v) {
;     ...
;   } else if (MODE == E_K) {
;     int lc = col & 1023;
;     *(GAS uint2*)((u16*)(ws + W_K) + (size_t)rl * 1024 + lc) = pack4(v);
;     int rg = g0 + rl;
;     float* o = rg < NPROMPT ? outp + O_KP + (size_t)rg * 1024 : outp + O_KS + (size_t)(rg - NPROMPT) * 1024;
;     __builtin_nontemporal_store(v, (GAS f32x4*)(o + lc));
	v_mov_b32_dpp v183, v65 row_ror:8 row_mask:0xf bank_mask:0x3
	v_add_u32_e32 v191, v246, v188
	v_add_u32_e32 v192, v246, v189
	global_store_dwordx4 v191, v[176:179], s[14:15] nt
	global_store_dwordx4 v192, v[180:183], s[14:15] nt
	v_permlane16_swap_b32_e32 v156, v158
	v_permlane16_swap_b32_e32 v157, v159
	global_store_dwordx4 v253, v[156:159], s[4:5] offset:256
	v_cvt_pk_bf16_f32 v148, v54, v55
	v_cvt_pk_bf16_f32 v149, v56, v57
	v_cvt_pk_bf16_f32 v150, v50, v51
	v_cvt_pk_bf16_f32 v151, v52, v53
	v_mov_b32_e32 v214, v54
	v_mov_b32_e32 v215, v55
	v_mov_b32_e32 v216, v56
	v_mov_b32_e32 v217, v57
	v_mov_b32_e32 v218, v50
	v_mov_b32_e32 v219, v51
	v_mov_b32_e32 v220, v52
	v_mov_b32_e32 v221, v53
	v_mov_b32_dpp v214, v50 row_ror:8 row_mask:0xf bank_mask:0xc
	v_mov_b32_dpp v215, v51 row_ror:8 row_mask:0xf bank_mask:0xc
	v_mov_b32_dpp v216, v52 row_ror:8 row_mask:0xf bank_mask:0xc
	v_mov_b32_dpp v217, v53 row_ror:8 row_mask:0xf bank_mask:0xc
	v_mov_b32_dpp v218, v54 row_ror:8 row_mask:0xf bank_mask:0x3
	v_mov_b32_dpp v219, v55 row_ror:8 row_mask:0xf bank_mask:0x3
	v_mov_b32_dpp v220, v56 row_ror:8 row_mask:0xf bank_mask:0x3
	v_mov_b32_dpp v221, v57 row_ror:8 row_mask:0xf bank_mask:0x3
	v_add_u32_e32 v191, v247, v188
	v_add_u32_e32 v192, v247, v189
	global_store_dwordx4 v191, v[214:217], s[14:15] nt
	global_store_dwordx4 v192, v[218:221], s[14:15] nt
	v_permlane16_swap_b32_e32 v144, v146
	v_permlane16_swap_b32_e32 v145, v147
	global_store_dwordx4 v250, v[144:147], s[8:9]
	v_cvt_pk_bf16_f32 v152, v46, v47
	v_cvt_pk_bf16_f32 v153, v48, v49
	v_cvt_pk_bf16_f32 v154, v42, v43
	v_cvt_pk_bf16_f32 v155, v44, v45
	v_mov_b32_e32 v176, v46
	v_mov_b32_e32 v177, v47
	v_mov_b32_e32 v178, v48
	v_mov_b32_e32 v179, v49
	v_mov_b32_e32 v180, v42
	v_mov_b32_e32 v181, v43
	v_mov_b32_e32 v182, v44
	v_mov_b32_e32 v183, v45
	v_mov_b32_dpp v176, v42 row_ror:8 row_mask:0xf bank_mask:0xc
	v_mov_b32_dpp v177, v43 row_ror:8 row_mask:0xf bank_mask:0xc
	v_mov_b32_dpp v178, v44 row_ror:8 row_mask:0xf bank_mask:0xc
	v_mov_b32_dpp v179, v45 row_ror:8 row_mask:0xf bank_mask:0xc
	v_mov_b32_dpp v180, v46 row_ror:8 row_mask:0xf bank_mask:0x3
	v_mov_b32_dpp v181, v47 row_ror:8 row_mask:0xf bank_mask:0x3
	v_mov_b32_dpp v182, v48 row_ror:8 row_mask:0xf bank_mask:0x3
	v_mov_b32_dpp v183, v49 row_ror:8 row_mask:0xf bank_mask:0x3
	v_add_u32_e32 v191, v248, v188
	v_add_u32_e32 v192, v248, v189
	global_store_dwordx4 v191, v[176:179], s[14:15] nt
	global_store_dwordx4 v192, v[180:183], s[14:15] nt
	v_permlane16_swap_b32_e32 v148, v150
	v_permlane16_swap_b32_e32 v149, v151
	global_store_dwordx4 v251, v[148:151], s[8:9]
	v_cvt_pk_bf16_f32 v156, v38, v39
	v_cvt_pk_bf16_f32 v157, v40, v41
	v_cvt_pk_bf16_f32 v158, v34, v35
	v_cvt_pk_bf16_f32 v159, v36, v37
	v_mov_b32_e32 v214, v38
	v_mov_b32_e32 v215, v39
	v_mov_b32_e32 v216, v40
	v_mov_b32_e32 v217, v41
	v_mov_b32_e32 v218, v34
	v_mov_b32_e32 v219, v35
	v_mov_b32_e32 v220, v36
	v_mov_b32_e32 v221, v37
	v_mov_b32_dpp v214, v34 row_ror:8 row_mask:0xf bank_mask:0xc
	v_mov_b32_dpp v215, v35 row_ror:8 row_mask:0xf bank_mask:0xc
	v_mov_b32_dpp v216, v36 row_ror:8 row_mask:0xf bank_mask:0xc
	v_mov_b32_dpp v217, v37 row_ror:8 row_mask:0xf bank_mask:0xc
	v_mov_b32_dpp v218, v38 row_ror:8 row_mask:0xf bank_mask:0x3
	v_mov_b32_dpp v219, v39 row_ror:8 row_mask:0xf bank_mask:0x3
	v_mov_b32_dpp v220, v40 row_ror:8 row_mask:0xf bank_mask:0x3
	v_mov_b32_dpp v221, v41 row_ror:8 row_mask:0xf bank_mask:0x3
	v_add_u32_e32 v191, v249, v188
	v_add_u32_e32 v192, v249, v189
	global_store_dwordx4 v191, v[214:217], s[14:15] nt
	global_store_dwordx4 v192, v[218:221], s[14:15] nt
	v_permlane16_swap_b32_e32 v152, v154
	v_permlane16_swap_b32_e32 v153, v155
	global_store_dwordx4 v252, v[152:155], s[8:9]
	v_cvt_pk_bf16_f32 v144, v30, v31
	v_cvt_pk_bf16_f32 v145, v32, v33
	v_cvt_pk_bf16_f32 v146, v26, v27
	v_cvt_pk_bf16_f32 v147, v28, v29
	v_mov_b32_e32 v176, v30
	v_mov_b32_e32 v177, v31
	v_mov_b32_e32 v178, v32
	v_mov_b32_e32 v179, v33
	v_mov_b32_e32 v180, v26
	v_mov_b32_e32 v181, v27
	v_mov_b32_e32 v182, v28
	v_mov_b32_e32 v183, v29
	v_mov_b32_dpp v176, v26 row_ror:8 row_mask:0xf bank_mask:0xc
	v_mov_b32_dpp v177, v27 row_ror:8 row_mask:0xf bank_mask:0xc
	v_mov_b32_dpp v178, v28 row_ror:8 row_mask:0xf bank_mask:0xc
; #define GAS __attribute__((address_space(1)))
; __device__ __forceinline__ uint2 pack4(f32x4 v) { return make_uint2(pack2(v[0], v[1]), pack2(v[2], v[3])); }
; template <int MODE>
; __device__ __forceinline__ void epi_elem(char* ws, float* outp, const float* b_gate, int g0, int rl, int col, f32x4 v) {
;     ...
;   } else if (MODE == E_K) {
;     int lc = col & 1023;
;     *(GAS uint2*)((u16*)(ws + W_K) + (size_t)rl * 1024 + lc) = pack4(v);
;     int rg = g0 + rl;
;     float* o = rg < NPROMPT ? outp + O_KP + (size_t)rg * 1024 : outp + O_KS + (size_t)(rg - NPROMPT) * 1024;
;     __builtin_nontemporal_store(v, (GAS f32x4*)(o + lc));
	v_mov_b32_dpp v179, v29 row_ror:8 row_mask:0xf bank_mask:0xc
	v_mov_b32_dpp v180, v30 row_ror:8 row_mask:0xf bank_mask:0x3
	v_mov_b32_dpp v181, v31 row_ror:8 row_mask:0xf bank_mask:0x3
	v_mov_b32_dpp v182, v32 row_ror:8 row_mask:0xf bank_mask:0x3
	v_mov_b32_dpp v183, v33 row_ror:8 row_mask:0xf bank_mask:0x3
	v_add_u32_e32 v191, v246, v188
	v_add_u32_e32 v192, v246, v189
	global_store_dwordx4 v191, v[176:179], s[14:15] offset:512 nt
	global_store_dwordx4 v192, v[180:183], s[14:15] offset:512 nt
	v_permlane16_swap_b32_e32 v156, v158
	v_permlane16_swap_b32_e32 v157, v159
	global_store_dwordx4 v253, v[156:159], s[8:9]
	v_cvt_pk_bf16_f32 v148, v22, v23
	v_cvt_pk_bf16_f32 v149, v24, v25
	v_cvt_pk_bf16_f32 v150, v18, v19
	v_cvt_pk_bf16_f32 v151, v20, v21
	v_mov_b32_e32 v214, v22
	v_mov_b32_e32 v215, v23
	v_mov_b32_e32 v216, v24
	v_mov_b32_e32 v217, v25
	v_mov_b32_e32 v218, v18
	v_mov_b32_e32 v219, v19
	v_mov_b32_e32 v220, v20
	v_mov_b32_e32 v221, v21
	v_mov_b32_dpp v214, v18 row_ror:8 row_mask:0xf bank_mask:0xc
	v_mov_b32_dpp v215, v19 row_ror:8 row_mask:0xf bank_mask:0xc
	v_mov_b32_dpp v216, v20 row_ror:8 row_mask:0xf bank_mask:0xc
	v_mov_b32_dpp v217, v21 row_ror:8 row_mask:0xf bank_mask:0xc
	v_mov_b32_dpp v218, v22 row_ror:8 row_mask:0xf bank_mask:0x3
	v_mov_b32_dpp v219, v23 row_ror:8 row_mask:0xf bank_mask:0x3
	v_mov_b32_dpp v220, v24 row_ror:8 row_mask:0xf bank_mask:0x3
	v_mov_b32_dpp v221, v25 row_ror:8 row_mask:0xf bank_mask:0x3
	v_add_u32_e32 v191, v247, v188
	v_add_u32_e32 v192, v247, v189
	global_store_dwordx4 v191, v[214:217], s[14:15] offset:512 nt
	global_store_dwordx4 v192, v[218:221], s[14:15] offset:512 nt
	v_permlane16_swap_b32_e32 v144, v146
	v_permlane16_swap_b32_e32 v145, v147
	global_store_dwordx4 v250, v[144:147], s[8:9] offset:256
	v_cvt_pk_bf16_f32 v152, v14, v15
	v_cvt_pk_bf16_f32 v153, v16, v17
	v_cvt_pk_bf16_f32 v154, v10, v11
	v_cvt_pk_bf16_f32 v155, v12, v13
	v_mov_b32_e32 v176, v14
	v_mov_b32_e32 v177, v15
	v_mov_b32_e32 v178, v16
	v_mov_b32_e32 v179, v17
	v_mov_b32_e32 v180, v10
	v_mov_b32_e32 v181, v11
	v_mov_b32_e32 v182, v12
	v_mov_b32_e32 v183, v13
	v_mov_b32_dpp v176, v10 row_ror:8 row_mask:0xf bank_mask:0xc
	v_mov_b32_dpp v177, v11 row_ror:8 row_mask:0xf bank_mask:0xc
	v_mov_b32_dpp v178, v12 row_ror:8 row_mask:0xf bank_mask:0xc
	v_mov_b32_dpp v179, v13 row_ror:8 row_mask:0xf bank_mask:0xc
	v_mov_b32_dpp v180, v14 row_ror:8 row_mask:0xf bank_mask:0x3
	v_mov_b32_dpp v181, v15 row_ror:8 row_mask:0xf bank_mask:0x3
	v_mov_b32_dpp v182, v16 row_ror:8 row_mask:0xf bank_mask:0x3
	v_mov_b32_dpp v183, v17 row_ror:8 row_mask:0xf bank_mask:0x3
	v_add_u32_e32 v191, v248, v188
	v_add_u32_e32 v192, v248, v189
	global_store_dwordx4 v191, v[176:179], s[14:15] offset:512 nt
	global_store_dwordx4 v192, v[180:183], s[14:15] offset:512 nt
	v_permlane16_swap_b32_e32 v148, v150
	v_permlane16_swap_b32_e32 v149, v151
	global_store_dwordx4 v251, v[148:151], s[8:9] offset:256
	v_cvt_pk_bf16_f32 v156, v6, v7
	v_cvt_pk_bf16_f32 v157, v8, v9
	v_cvt_pk_bf16_f32 v158, v2, v3
	v_cvt_pk_bf16_f32 v159, v4, v5
	v_mov_b32_e32 v214, v6
	v_mov_b32_e32 v215, v7
	v_mov_b32_e32 v216, v8
	v_mov_b32_e32 v217, v9
	v_mov_b32_e32 v218, v2
	v_mov_b32_e32 v219, v3
	v_mov_b32_e32 v220, v4
	v_mov_b32_e32 v221, v5
	v_mov_b32_dpp v214, v2 row_ror:8 row_mask:0xf bank_mask:0xc
	v_mov_b32_dpp v215, v3 row_ror:8 row_mask:0xf bank_mask:0xc
	v_mov_b32_dpp v216, v4 row_ror:8 row_mask:0xf bank_mask:0xc
	v_mov_b32_dpp v217, v5 row_ror:8 row_mask:0xf bank_mask:0xc
	v_mov_b32_dpp v218, v6 row_ror:8 row_mask:0xf bank_mask:0x3
	v_mov_b32_dpp v219, v7 row_ror:8 row_mask:0xf bank_mask:0x3
	v_mov_b32_dpp v220, v8 row_ror:8 row_mask:0xf bank_mask:0x3
	v_mov_b32_dpp v221, v9 row_ror:8 row_mask:0xf bank_mask:0x3
	v_add_u32_e32 v191, v249, v188
	v_add_u32_e32 v192, v249, v189
	global_store_dwordx4 v191, v[214:217], s[14:15] offset:512 nt
	global_store_dwordx4 v192, v[218:221], s[14:15] offset:512 nt
	v_permlane16_swap_b32_e32 v152, v154
	v_permlane16_swap_b32_e32 v153, v155
	global_store_dwordx4 v252, v[152:155], s[8:9] offset:256
	s_nop 1
	v_permlane16_swap_b32_e32 v156, v158
	v_permlane16_swap_b32_e32 v157, v159
	global_store_dwordx4 v253, v[156:159], s[8:9] offset:256
	s_branch .LBB0_619
